# exp block as a 4-stage pipeline (8 values per stage): each stage's exps interleaved with the previous stage's bf16 packing and row-sum adds
# baseline (speedup 1.0000x reference)
; #define SBAR() __builtin_amdgcn_sched_barrier(0)
; #define PK4(P, BASE, OUT) do { u32x4 w = {cvtpk_a(P[BASE + 0], P[BASE + 1]), cvtpk_a(P[BASE + 2], P[BASE + 3]), cvtpk_a(P[BASE + 4], P[BASE + 5]), cvtpk_a(P[BASE + 6], P[BASE + 7])}; \
;     OUT = *reinterpret_cast<bf16x8*>(&w); } while (0)
; #define SWAIT() asm volatile("s_waitcnt vmcnt(3)" ::: "memory")
; __device__ __forceinline__ float exp_pack(f32x16& p0, f32x16& p1, bf16x8& pa0, bf16x8& pa1, bf16x8& pa2, bf16x8& pa3) {
; #pragma unroll
;     for (int r = 0; r < 16; ++r) p0[r] = __builtin_amdgcn_exp2f(p0[r]);
; #pragma unroll
;     for (int r = 0; r < 16; ++r) p1[r] = __builtin_amdgcn_exp2f(p1[r]);
;     SBAR(); asm volatile("s_nop 1" ::: "memory"); SBAR();
;     ...
;     PK4(p0, 0, pa0); PK4(p0, 8, pa1); PK4(p1, 0, pa2); PK4(p1, 8, pa3);
;     ...
;     float ps0 = p0[0], ps1 = p1[0];
; #pragma unroll
;     for (int r = 1; r < 16; ++r) { ps0 += p0[r]; ps1 += p1[r]; }
;     float ps = ps0 + ps1;
;     { auto rr = __builtin_amdgcn_permlane32_swap(__float_as_uint(ps), __float_as_uint(ps), false, false);
;       ps = __uint_as_float(rr[0]) + __uint_as_float(rr[1]); }
;     return ps;
; template <bool MLA>
; __device__ __forceinline__ void attn_core(const bf16_t* __restrict__ Qb, const bf16_t* __restrict__ Kh, const bf16_t* __restrict__ Vh, int seq, char* lds,
;                                           f32x16 (&o)[Cfg<MLA>::NCB], const int wid  , const int g  ) {
;     ...
;         SWAIT(); if (j + 2 < NT) SWRITE(((j + 2) % 3) * SHM_K, ((j + 2) & 3) * SHM_V, SE);
.LBB0_1162:
	v_exp_f32_e32 v96, v96
	v_exp_f32_e32 v97, v97
	v_exp_f32_e32 v98, v98
	v_exp_f32_e32 v99, v99
	v_exp_f32_e32 v100, v100
	v_exp_f32_e32 v101, v101
	v_exp_f32_e32 v102, v102
	v_exp_f32_e32 v103, v103
	v_exp_f32_e32 v104, v104
	v_cvt_pk_bf16_f32 v180, v96, v97
	v_exp_f32_e32 v105, v105
	v_add_f32_e32 v96, v96, v97
	v_add_f32_e32 v96, v98, v96
	v_exp_f32_e32 v106, v106
	v_cvt_pk_bf16_f32 v181, v98, v99
	v_exp_f32_e32 v107, v107
	v_add_f32_e32 v96, v99, v96
	v_add_f32_e32 v96, v100, v96
	v_exp_f32_e32 v108, v108
	v_cvt_pk_bf16_f32 v182, v100, v101
	v_exp_f32_e32 v109, v109
	v_add_f32_e32 v96, v101, v96
	v_add_f32_e32 v96, v102, v96
	v_exp_f32_e32 v110, v110
	v_cvt_pk_bf16_f32 v183, v102, v103
	v_exp_f32_e32 v111, v111
	v_add_f32_e32 v96, v103, v96
	v_exp_f32_e32 v80, v80
	v_cvt_pk_bf16_f32 v176, v104, v105
	v_exp_f32_e32 v81, v81
	v_add_f32_e32 v104, v104, v105
	v_add_f32_e32 v104, v106, v104
	v_exp_f32_e32 v82, v82
	v_cvt_pk_bf16_f32 v177, v106, v107
	v_exp_f32_e32 v83, v83
	v_add_f32_e32 v104, v107, v104
	v_add_f32_e32 v104, v108, v104
	v_exp_f32_e32 v84, v84
	v_cvt_pk_bf16_f32 v178, v108, v109
	v_exp_f32_e32 v85, v85
	v_add_f32_e32 v104, v109, v104
	v_add_f32_e32 v104, v110, v104
	v_exp_f32_e32 v86, v86
	v_cvt_pk_bf16_f32 v179, v110, v111
	v_exp_f32_e32 v87, v87
	v_add_f32_e32 v104, v111, v104
	v_exp_f32_e32 v88, v88
	v_cvt_pk_bf16_f32 v172, v80, v81
	v_exp_f32_e32 v89, v89
	v_add_f32_e32 v80, v80, v81
	v_add_f32_e32 v80, v82, v80
	v_exp_f32_e32 v90, v90
	v_cvt_pk_bf16_f32 v173, v82, v83
	v_exp_f32_e32 v91, v91
	v_add_f32_e32 v80, v83, v80
	v_add_f32_e32 v80, v84, v80
	v_exp_f32_e32 v92, v92
	v_cvt_pk_bf16_f32 v174, v84, v85
	v_exp_f32_e32 v93, v93
	v_add_f32_e32 v80, v85, v80
	v_add_f32_e32 v80, v86, v80
	v_exp_f32_e32 v94, v94
	v_cvt_pk_bf16_f32 v175, v86, v87
	v_exp_f32_e32 v95, v95
	v_add_f32_e32 v80, v87, v80
	v_cvt_pk_bf16_f32 v168, v88, v89
	v_add_f32_e32 v88, v88, v89
	v_add_f32_e32 v88, v90, v88
	v_cvt_pk_bf16_f32 v169, v90, v91
	v_add_f32_e32 v88, v91, v88
	v_add_f32_e32 v88, v92, v88
	v_cvt_pk_bf16_f32 v170, v92, v93
	v_add_f32_e32 v88, v93, v88
	v_add_f32_e32 v88, v94, v88
	v_cvt_pk_bf16_f32 v171, v94, v95
	v_add_f32_e32 v88, v95, v88
	v_add_f32_e32 v96, v96, v104
	v_add_f32_e32 v80, v80, v88
	v_add_f32_e32 v185, v80, v96
	s_waitcnt vmcnt(3)
	s_cmpk_gt_u32 s95, 0x81
	s_cbranch_scc1 .LBB0_1164
	s_add_i32 s0, s51, 0x8000
	s_and_b32 s0, s0, 0x8000
	s_add_i32 s0, s0, 0
	v_add_u32_e32 v80, s0, v210
	s_waitcnt vmcnt(5)
	ds_write_b128 v80, v[132:135]
	v_add_u32_e32 v80, s0, v211
	s_add_i32 s0, s94, 0xffff
	s_mul_i32 s1, s0, 0xab
	s_bfe_u32 s1, s1, 0x70009
	s_mul_i32 s1, s1, 3
	s_sub_i32 s0, s0, s1
	s_and_b32 s0, s0, 0xff
	s_mulk_i32 s0, 0x2400
	s_waitcnt vmcnt(4)
	ds_write_b128 v80, v[128:131]
	v_add_u32_e32 v80, s0, v212
	s_waitcnt vmcnt(3)
	ds_write_b128 v80, v[136:139]

; #define SBAR() __builtin_amdgcn_sched_barrier(0)
; #define PK4(P, BASE, OUT) do { u32x4 w = {cvtpk_a(P[BASE + 0], P[BASE + 1]), cvtpk_a(P[BASE + 2], P[BASE + 3]), cvtpk_a(P[BASE + 4], P[BASE + 5]), cvtpk_a(P[BASE + 6], P[BASE + 7])}; \
;     OUT = *reinterpret_cast<bf16x8*>(&w); } while (0)
; #define SWAIT() asm volatile("s_waitcnt vmcnt(3)" ::: "memory")
; __device__ __forceinline__ float exp_pack(f32x16& p0, f32x16& p1, bf16x8& pa0, bf16x8& pa1, bf16x8& pa2, bf16x8& pa3) {
; #pragma unroll
;     for (int r = 0; r < 16; ++r) p0[r] = __builtin_amdgcn_exp2f(p0[r]);
; #pragma unroll
;     for (int r = 0; r < 16; ++r) p1[r] = __builtin_amdgcn_exp2f(p1[r]);
;     SBAR(); asm volatile("s_nop 1" ::: "memory"); SBAR();
;     ...
;     PK4(p0, 0, pa0); PK4(p0, 8, pa1); PK4(p1, 0, pa2); PK4(p1, 8, pa3);
;     ...
;     float ps0 = p0[0], ps1 = p1[0];
; #pragma unroll
;     for (int r = 1; r < 16; ++r) { ps0 += p0[r]; ps1 += p1[r]; }
;     float ps = ps0 + ps1;
;     { auto rr = __builtin_amdgcn_permlane32_swap(__float_as_uint(ps), __float_as_uint(ps), false, false);
;       ps = __uint_as_float(rr[0]) + __uint_as_float(rr[1]); }
;     return ps;
; template <bool MLA>
; __device__ __forceinline__ void attn_core(const bf16_t* __restrict__ Qb, const bf16_t* __restrict__ Kh, const bf16_t* __restrict__ Vh, int seq, char* lds,
;                                           f32x16 (&o)[Cfg<MLA>::NCB], const int wid  , const int g  ) {
;     ...
;         SWAIT(); if (j + 3 < NT) SWRITE(((j + 3) % 3) * SHM_K, ((j + 3) & 3) * SHM_V, SO);
.LBB0_1169:
	v_exp_f32_e32 v96, v96
	v_exp_f32_e32 v97, v97
	v_exp_f32_e32 v98, v98
	v_exp_f32_e32 v99, v99
	v_exp_f32_e32 v100, v100
	v_exp_f32_e32 v101, v101
	v_exp_f32_e32 v102, v102
	v_exp_f32_e32 v103, v103
	v_exp_f32_e32 v104, v104
	v_cvt_pk_bf16_f32 v180, v96, v97
	v_exp_f32_e32 v105, v105
	v_add_f32_e32 v96, v96, v97
	v_add_f32_e32 v96, v98, v96
	v_exp_f32_e32 v106, v106
	v_cvt_pk_bf16_f32 v181, v98, v99
	v_exp_f32_e32 v107, v107
	v_add_f32_e32 v96, v99, v96
	v_add_f32_e32 v96, v100, v96
	v_exp_f32_e32 v108, v108
	v_cvt_pk_bf16_f32 v182, v100, v101
	v_exp_f32_e32 v109, v109
	v_add_f32_e32 v96, v101, v96
	v_add_f32_e32 v96, v102, v96
	v_exp_f32_e32 v110, v110
	v_cvt_pk_bf16_f32 v183, v102, v103
	v_exp_f32_e32 v111, v111
	v_add_f32_e32 v96, v103, v96
	v_exp_f32_e32 v80, v80
	v_cvt_pk_bf16_f32 v176, v104, v105
	v_exp_f32_e32 v81, v81
	v_add_f32_e32 v104, v104, v105
	v_add_f32_e32 v104, v106, v104
	v_exp_f32_e32 v82, v82
	v_cvt_pk_bf16_f32 v177, v106, v107
	v_exp_f32_e32 v83, v83
	v_add_f32_e32 v104, v107, v104
	v_add_f32_e32 v104, v108, v104
	v_exp_f32_e32 v84, v84
	v_cvt_pk_bf16_f32 v178, v108, v109
	v_exp_f32_e32 v85, v85
	v_add_f32_e32 v104, v109, v104
	v_add_f32_e32 v104, v110, v104
	v_exp_f32_e32 v86, v86
	v_cvt_pk_bf16_f32 v179, v110, v111
	v_exp_f32_e32 v87, v87
	v_add_f32_e32 v104, v111, v104
	v_exp_f32_e32 v88, v88
	v_cvt_pk_bf16_f32 v172, v80, v81
	v_exp_f32_e32 v89, v89
	v_add_f32_e32 v80, v80, v81
	v_add_f32_e32 v80, v82, v80
	v_exp_f32_e32 v90, v90
	v_cvt_pk_bf16_f32 v173, v82, v83
	v_exp_f32_e32 v91, v91
	v_add_f32_e32 v80, v83, v80
	v_add_f32_e32 v80, v84, v80
	v_exp_f32_e32 v92, v92
	v_cvt_pk_bf16_f32 v174, v84, v85
	v_exp_f32_e32 v93, v93
	v_add_f32_e32 v80, v85, v80
	v_add_f32_e32 v80, v86, v80
	v_exp_f32_e32 v94, v94
	v_cvt_pk_bf16_f32 v175, v86, v87
	v_exp_f32_e32 v95, v95
	v_add_f32_e32 v80, v87, v80
	v_cvt_pk_bf16_f32 v168, v88, v89
	v_add_f32_e32 v88, v88, v89
	v_add_f32_e32 v88, v90, v88
	v_cvt_pk_bf16_f32 v169, v90, v91
	v_add_f32_e32 v88, v91, v88
	v_add_f32_e32 v88, v92, v88
	v_cvt_pk_bf16_f32 v170, v92, v93
	v_add_f32_e32 v88, v93, v88
	v_add_f32_e32 v88, v94, v88
	v_cvt_pk_bf16_f32 v171, v94, v95
	v_add_f32_e32 v88, v95, v88
	v_add_f32_e32 v96, v96, v104
	v_add_f32_e32 v80, v80, v88
	v_add_f32_e32 v80, v80, v96
	s_waitcnt vmcnt(3)
	s_cmpk_gt_u32 s95, 0x80
	s_cbranch_scc1 .LBB0_1149
	s_add_i32 s0, s96, 0
	v_add_u32_e32 v82, s0, v210
	s_waitcnt vmcnt(5)
	ds_write_b128 v82, v[140:143]
	v_add_u32_e32 v82, s0, v211
	s_mul_i32 s0, s94, 0xab
	s_bfe_u32 s0, s0, 0x70009
	s_mul_i32 s0, s0, 3
	s_sub_i32 s0, s94, s0
	s_and_b32 s0, s0, 0xff
	s_mulk_i32 s0, 0x2400
	s_waitcnt vmcnt(4)
	ds_write_b128 v82, v[144:147]
	v_add_u32_e32 v82, s0, v212
	s_waitcnt vmcnt(3)
	ds_write_b128 v82, v[148:151]
	s_branch .LBB0_1149

; #define SBAR() __builtin_amdgcn_sched_barrier(0)
; #define PK4(P, BASE, OUT) do { u32x4 w = {cvtpk_a(P[BASE + 0], P[BASE + 1]), cvtpk_a(P[BASE + 2], P[BASE + 3]), cvtpk_a(P[BASE + 4], P[BASE + 5]), cvtpk_a(P[BASE + 6], P[BASE + 7])}; \
;     OUT = *reinterpret_cast<bf16x8*>(&w); } while (0)
; #define SWAIT() asm volatile("s_waitcnt vmcnt(3)" ::: "memory")
; __device__ __forceinline__ float exp_pack(f32x16& p0, f32x16& p1, bf16x8& pa0, bf16x8& pa1, bf16x8& pa2, bf16x8& pa3) {
; #pragma unroll
;     for (int r = 0; r < 16; ++r) p0[r] = __builtin_amdgcn_exp2f(p0[r]);
; #pragma unroll
;     for (int r = 0; r < 16; ++r) p1[r] = __builtin_amdgcn_exp2f(p1[r]);
;     SBAR(); asm volatile("s_nop 1" ::: "memory"); SBAR();
;     ...
;     PK4(p0, 0, pa0); PK4(p0, 8, pa1); PK4(p1, 0, pa2); PK4(p1, 8, pa3);
;     ...
;     float ps0 = p0[0], ps1 = p1[0];
; #pragma unroll
;     for (int r = 1; r < 16; ++r) { ps0 += p0[r]; ps1 += p1[r]; }
;     float ps = ps0 + ps1;
;     { auto rr = __builtin_amdgcn_permlane32_swap(__float_as_uint(ps), __float_as_uint(ps), false, false);
;       ps = __uint_as_float(rr[0]) + __uint_as_float(rr[1]); }
;     return ps;
; template <bool MLA>
; __device__ __forceinline__ void attn_core(const bf16_t* __restrict__ Qb, const bf16_t* __restrict__ Kh, const bf16_t* __restrict__ Vh, int seq, char* lds,
;                                           f32x16 (&o)[Cfg<MLA>::NCB], const int wid  , const int g  ) {
;     ...
;         SWAIT(); if (j + 2 < NT) SWRITE(((j + 2) % 3) * SHM_K, ((j + 2) & 3) * SHM_V, SE);
.LBB0_1193:
	v_exp_f32_e32 v96, v96
	v_exp_f32_e32 v97, v97
	v_exp_f32_e32 v98, v98
	v_exp_f32_e32 v99, v99
	v_exp_f32_e32 v100, v100
	v_exp_f32_e32 v101, v101
	v_exp_f32_e32 v102, v102
	v_exp_f32_e32 v103, v103
	v_exp_f32_e32 v104, v104
	v_cvt_pk_bf16_f32 v180, v96, v97
	v_exp_f32_e32 v105, v105
	v_add_f32_e32 v96, v96, v97
	v_add_f32_e32 v96, v98, v96
	v_exp_f32_e32 v106, v106
	v_cvt_pk_bf16_f32 v181, v98, v99
	v_exp_f32_e32 v107, v107
	v_add_f32_e32 v96, v99, v96
	v_add_f32_e32 v96, v100, v96
	v_exp_f32_e32 v108, v108
	v_cvt_pk_bf16_f32 v182, v100, v101
	v_exp_f32_e32 v109, v109
	v_add_f32_e32 v96, v101, v96
	v_add_f32_e32 v96, v102, v96
	v_exp_f32_e32 v110, v110
	v_cvt_pk_bf16_f32 v183, v102, v103
	v_exp_f32_e32 v111, v111
	v_add_f32_e32 v96, v103, v96
	v_exp_f32_e32 v80, v80
	v_cvt_pk_bf16_f32 v176, v104, v105
	v_exp_f32_e32 v81, v81
	v_add_f32_e32 v104, v104, v105
	v_add_f32_e32 v104, v106, v104
	v_exp_f32_e32 v82, v82
	v_cvt_pk_bf16_f32 v177, v106, v107
	v_exp_f32_e32 v83, v83
	v_add_f32_e32 v104, v107, v104
	v_add_f32_e32 v104, v108, v104
	v_exp_f32_e32 v84, v84
	v_cvt_pk_bf16_f32 v178, v108, v109
	v_exp_f32_e32 v85, v85
	v_add_f32_e32 v104, v109, v104
	v_add_f32_e32 v104, v110, v104
	v_exp_f32_e32 v86, v86
	v_cvt_pk_bf16_f32 v179, v110, v111
	v_exp_f32_e32 v87, v87
	v_add_f32_e32 v104, v111, v104
	v_exp_f32_e32 v88, v88
	v_cvt_pk_bf16_f32 v172, v80, v81
	v_exp_f32_e32 v89, v89
	v_add_f32_e32 v80, v80, v81
	v_add_f32_e32 v80, v82, v80
	v_exp_f32_e32 v90, v90
	v_cvt_pk_bf16_f32 v173, v82, v83
	v_exp_f32_e32 v91, v91
	v_add_f32_e32 v80, v83, v80
	v_add_f32_e32 v80, v84, v80
	v_exp_f32_e32 v92, v92
	v_cvt_pk_bf16_f32 v174, v84, v85
	v_exp_f32_e32 v93, v93
	v_add_f32_e32 v80, v85, v80
	v_add_f32_e32 v80, v86, v80
	v_exp_f32_e32 v94, v94
	v_cvt_pk_bf16_f32 v175, v86, v87
	v_exp_f32_e32 v95, v95
	v_add_f32_e32 v80, v87, v80
	v_cvt_pk_bf16_f32 v168, v88, v89
	v_add_f32_e32 v88, v88, v89
	v_add_f32_e32 v88, v90, v88
	v_cvt_pk_bf16_f32 v169, v90, v91
	v_add_f32_e32 v88, v91, v88
	v_add_f32_e32 v88, v92, v88
	v_cvt_pk_bf16_f32 v170, v92, v93
	v_add_f32_e32 v88, v93, v88
	v_add_f32_e32 v88, v94, v88
	v_cvt_pk_bf16_f32 v171, v94, v95
	v_add_f32_e32 v88, v95, v88
	v_add_f32_e32 v96, v96, v104
	v_add_f32_e32 v80, v80, v88
	v_add_f32_e32 v185, v80, v96
	s_waitcnt vmcnt(3)
	s_cmpk_gt_u32 s64, 0x81
	s_cbranch_scc1 .LBB0_1195
	s_add_i32 s0, s51, 0x8000
	s_and_b32 s0, s0, 0x8000
	s_add_i32 s0, s0, 0
	v_add_u32_e32 v80, s0, v210
	s_waitcnt vmcnt(5)
	ds_write_b128 v80, v[132:135]
	v_add_u32_e32 v80, s0, v211
	s_add_i32 s0, s7, 0xffff
	s_mul_i32 s1, s0, 0xab
	s_bfe_u32 s1, s1, 0x70009
	s_mul_i32 s1, s1, 3
	s_sub_i32 s0, s0, s1
	s_and_b32 s0, s0, 0xff
	s_mulk_i32 s0, 0x2400
	s_waitcnt vmcnt(4)
	ds_write_b128 v80, v[128:131]
	v_add_u32_e32 v80, s0, v212
	s_waitcnt vmcnt(3)
	ds_write_b128 v80, v[136:139]

; #define SBAR() __builtin_amdgcn_sched_barrier(0)
; #define PK4(P, BASE, OUT) do { u32x4 w = {cvtpk_a(P[BASE + 0], P[BASE + 1]), cvtpk_a(P[BASE + 2], P[BASE + 3]), cvtpk_a(P[BASE + 4], P[BASE + 5]), cvtpk_a(P[BASE + 6], P[BASE + 7])}; \
;     OUT = *reinterpret_cast<bf16x8*>(&w); } while (0)
; #define SWAIT() asm volatile("s_waitcnt vmcnt(3)" ::: "memory")
; __device__ __forceinline__ float exp_pack(f32x16& p0, f32x16& p1, bf16x8& pa0, bf16x8& pa1, bf16x8& pa2, bf16x8& pa3) {
; #pragma unroll
;     for (int r = 0; r < 16; ++r) p0[r] = __builtin_amdgcn_exp2f(p0[r]);
; #pragma unroll
;     for (int r = 0; r < 16; ++r) p1[r] = __builtin_amdgcn_exp2f(p1[r]);
;     SBAR(); asm volatile("s_nop 1" ::: "memory"); SBAR();
;     ...
;     PK4(p0, 0, pa0); PK4(p0, 8, pa1); PK4(p1, 0, pa2); PK4(p1, 8, pa3);
;     ...
;     float ps0 = p0[0], ps1 = p1[0];
; #pragma unroll
;     for (int r = 1; r < 16; ++r) { ps0 += p0[r]; ps1 += p1[r]; }
;     float ps = ps0 + ps1;
;     { auto rr = __builtin_amdgcn_permlane32_swap(__float_as_uint(ps), __float_as_uint(ps), false, false);
;       ps = __uint_as_float(rr[0]) + __uint_as_float(rr[1]); }
;     return ps;
; template <bool MLA>
; __device__ __forceinline__ void attn_core(const bf16_t* __restrict__ Qb, const bf16_t* __restrict__ Kh, const bf16_t* __restrict__ Vh, int seq, char* lds,
;                                           f32x16 (&o)[Cfg<MLA>::NCB], const int wid  , const int g  ) {
;     ...
;         SWAIT(); if (j + 3 < NT) SWRITE(((j + 3) % 3) * SHM_K, ((j + 3) & 3) * SHM_V, SO);
.LBB0_1200:
	v_exp_f32_e32 v96, v96
	v_exp_f32_e32 v97, v97
	v_exp_f32_e32 v98, v98
	v_exp_f32_e32 v99, v99
	v_exp_f32_e32 v100, v100
	v_exp_f32_e32 v101, v101
	v_exp_f32_e32 v102, v102
	v_exp_f32_e32 v103, v103
	v_exp_f32_e32 v104, v104
	v_cvt_pk_bf16_f32 v180, v96, v97
	v_exp_f32_e32 v105, v105
	v_add_f32_e32 v96, v96, v97
	v_add_f32_e32 v96, v98, v96
	v_exp_f32_e32 v106, v106
	v_cvt_pk_bf16_f32 v181, v98, v99
	v_exp_f32_e32 v107, v107
	v_add_f32_e32 v96, v99, v96
	v_add_f32_e32 v96, v100, v96
	v_exp_f32_e32 v108, v108
	v_cvt_pk_bf16_f32 v182, v100, v101
	v_exp_f32_e32 v109, v109
	v_add_f32_e32 v96, v101, v96
	v_add_f32_e32 v96, v102, v96
	v_exp_f32_e32 v110, v110
	v_cvt_pk_bf16_f32 v183, v102, v103
	v_exp_f32_e32 v111, v111
	v_add_f32_e32 v96, v103, v96
	v_exp_f32_e32 v80, v80
	v_cvt_pk_bf16_f32 v176, v104, v105
	v_exp_f32_e32 v81, v81
	v_add_f32_e32 v104, v104, v105
	v_add_f32_e32 v104, v106, v104
	v_exp_f32_e32 v82, v82
	v_cvt_pk_bf16_f32 v177, v106, v107
	v_exp_f32_e32 v83, v83
	v_add_f32_e32 v104, v107, v104
	v_add_f32_e32 v104, v108, v104
	v_exp_f32_e32 v84, v84
	v_cvt_pk_bf16_f32 v178, v108, v109
	v_exp_f32_e32 v85, v85
	v_add_f32_e32 v104, v109, v104
	v_add_f32_e32 v104, v110, v104
	v_exp_f32_e32 v86, v86
	v_cvt_pk_bf16_f32 v179, v110, v111
	v_exp_f32_e32 v87, v87
	v_add_f32_e32 v104, v111, v104
	v_exp_f32_e32 v88, v88
	v_cvt_pk_bf16_f32 v172, v80, v81
	v_exp_f32_e32 v89, v89
	v_add_f32_e32 v80, v80, v81
	v_add_f32_e32 v80, v82, v80
	v_exp_f32_e32 v90, v90
	v_cvt_pk_bf16_f32 v173, v82, v83
	v_exp_f32_e32 v91, v91
	v_add_f32_e32 v80, v83, v80
	v_add_f32_e32 v80, v84, v80
	v_exp_f32_e32 v92, v92
	v_cvt_pk_bf16_f32 v174, v84, v85
	v_exp_f32_e32 v93, v93
	v_add_f32_e32 v80, v85, v80
	v_add_f32_e32 v80, v86, v80
	v_exp_f32_e32 v94, v94
	v_cvt_pk_bf16_f32 v175, v86, v87
	v_exp_f32_e32 v95, v95
	v_add_f32_e32 v80, v87, v80
	v_cvt_pk_bf16_f32 v168, v88, v89
	v_add_f32_e32 v88, v88, v89
	v_add_f32_e32 v88, v90, v88
	v_cvt_pk_bf16_f32 v169, v90, v91
	v_add_f32_e32 v88, v91, v88
	v_add_f32_e32 v88, v92, v88
	v_cvt_pk_bf16_f32 v170, v92, v93
	v_add_f32_e32 v88, v93, v88
	v_add_f32_e32 v88, v94, v88
	v_cvt_pk_bf16_f32 v171, v94, v95
	v_add_f32_e32 v88, v95, v88
	v_add_f32_e32 v96, v96, v104
	v_add_f32_e32 v80, v80, v88
	v_add_f32_e32 v80, v80, v96
	s_waitcnt vmcnt(3)
	s_cmpk_gt_u32 s64, 0x80
	s_cbranch_scc1 .LBB0_1180
	s_add_i32 s0, s65, 0
	v_add_u32_e32 v82, s0, v210
	s_waitcnt vmcnt(5)
	ds_write_b128 v82, v[140:143]
	v_add_u32_e32 v82, s0, v211
	s_mul_i32 s0, s7, 0xab
	s_bfe_u32 s0, s0, 0x70009
	s_mul_i32 s0, s0, 3
	s_sub_i32 s0, s7, s0
	s_and_b32 s0, s0, 0xff
	s_mulk_i32 s0, 0x2400
	s_waitcnt vmcnt(4)
	ds_write_b128 v82, v[144:147]
	v_add_u32_e32 v82, s0, v212
	s_waitcnt vmcnt(3)
	ds_write_b128 v82, v[148:151]
	s_branch .LBB0_1180

; #define SBAR() __builtin_amdgcn_sched_barrier(0)
; #define PK4(P, BASE, OUT) do { u32x4 w = {cvtpk_a(P[BASE + 0], P[BASE + 1]), cvtpk_a(P[BASE + 2], P[BASE + 3]), cvtpk_a(P[BASE + 4], P[BASE + 5]), cvtpk_a(P[BASE + 6], P[BASE + 7])}; \
;     OUT = *reinterpret_cast<bf16x8*>(&w); } while (0)
; #define SWAIT() asm volatile("s_waitcnt vmcnt(3)" ::: "memory")
; __device__ __forceinline__ float exp_pack(f32x16& p0, f32x16& p1, bf16x8& pa0, bf16x8& pa1, bf16x8& pa2, bf16x8& pa3) {
; #pragma unroll
;     for (int r = 0; r < 16; ++r) p0[r] = __builtin_amdgcn_exp2f(p0[r]);
; #pragma unroll
;     for (int r = 0; r < 16; ++r) p1[r] = __builtin_amdgcn_exp2f(p1[r]);
;     SBAR(); asm volatile("s_nop 1" ::: "memory"); SBAR();
;     ...
;     PK4(p0, 0, pa0); PK4(p0, 8, pa1); PK4(p1, 0, pa2); PK4(p1, 8, pa3);
;     ...
;     float ps0 = p0[0], ps1 = p1[0];
; #pragma unroll
;     for (int r = 1; r < 16; ++r) { ps0 += p0[r]; ps1 += p1[r]; }
;     float ps = ps0 + ps1;
;     { auto rr = __builtin_amdgcn_permlane32_swap(__float_as_uint(ps), __float_as_uint(ps), false, false);
;       ps = __uint_as_float(rr[0]) + __uint_as_float(rr[1]); }
;     return ps;
; template <bool MLA>
; __device__ __forceinline__ void attn_core(const bf16_t* __restrict__ Qb, const bf16_t* __restrict__ Kh, const bf16_t* __restrict__ Vh, int seq, char* lds,
;                                           f32x16 (&o)[Cfg<MLA>::NCB], const int wid  , const int g  ) {
;     ...
;         SWAIT(); if (j + 2 < NT) SWRITE(((j + 2) % 3) * SHM_K, ((j + 2) & 3) * SHM_V, SE);
.LBB0_1233:
	v_exp_f32_e32 v64, v64
	v_exp_f32_e32 v65, v65
	v_exp_f32_e32 v66, v66
	v_exp_f32_e32 v67, v67
	v_exp_f32_e32 v68, v68
	v_exp_f32_e32 v69, v69
	v_exp_f32_e32 v70, v70
	v_exp_f32_e32 v71, v71
	v_exp_f32_e32 v72, v72
	v_cvt_pk_bf16_f32 v140, v64, v65
	v_exp_f32_e32 v73, v73
	v_add_f32_e32 v64, v64, v65
	v_add_f32_e32 v64, v66, v64
	v_exp_f32_e32 v74, v74
	v_cvt_pk_bf16_f32 v141, v66, v67
	v_exp_f32_e32 v75, v75
	v_add_f32_e32 v64, v67, v64
	v_add_f32_e32 v64, v68, v64
	v_exp_f32_e32 v76, v76
	v_cvt_pk_bf16_f32 v142, v68, v69
	v_exp_f32_e32 v77, v77
	v_add_f32_e32 v64, v69, v64
	v_add_f32_e32 v64, v70, v64
	v_exp_f32_e32 v78, v78
	v_cvt_pk_bf16_f32 v143, v70, v71
	v_exp_f32_e32 v79, v79
	v_add_f32_e32 v64, v71, v64
	v_exp_f32_e32 v48, v48
	v_cvt_pk_bf16_f32 v136, v72, v73
	v_exp_f32_e32 v49, v49
	v_add_f32_e32 v72, v72, v73
	v_add_f32_e32 v72, v74, v72
	v_exp_f32_e32 v50, v50
	v_cvt_pk_bf16_f32 v137, v74, v75
	v_exp_f32_e32 v51, v51
	v_add_f32_e32 v72, v75, v72
	v_add_f32_e32 v72, v76, v72
	v_exp_f32_e32 v52, v52
	v_cvt_pk_bf16_f32 v138, v76, v77
	v_exp_f32_e32 v53, v53
	v_add_f32_e32 v72, v77, v72
	v_add_f32_e32 v72, v78, v72
	v_exp_f32_e32 v54, v54
	v_cvt_pk_bf16_f32 v139, v78, v79
	v_exp_f32_e32 v55, v55
	v_add_f32_e32 v72, v79, v72
	v_exp_f32_e32 v56, v56
	v_cvt_pk_bf16_f32 v132, v48, v49
	v_exp_f32_e32 v57, v57
	v_add_f32_e32 v48, v48, v49
	v_add_f32_e32 v48, v50, v48
	v_exp_f32_e32 v58, v58
	v_cvt_pk_bf16_f32 v133, v50, v51
	v_exp_f32_e32 v59, v59
	v_add_f32_e32 v48, v51, v48
	v_add_f32_e32 v48, v52, v48
	v_exp_f32_e32 v60, v60
	v_cvt_pk_bf16_f32 v134, v52, v53
	v_exp_f32_e32 v61, v61
	v_add_f32_e32 v48, v53, v48
	v_add_f32_e32 v48, v54, v48
	v_exp_f32_e32 v62, v62
	v_cvt_pk_bf16_f32 v135, v54, v55
	v_exp_f32_e32 v63, v63
	v_add_f32_e32 v48, v55, v48
	v_cvt_pk_bf16_f32 v128, v56, v57
	v_add_f32_e32 v56, v56, v57
	v_add_f32_e32 v56, v58, v56
	v_cvt_pk_bf16_f32 v129, v58, v59
	v_add_f32_e32 v56, v59, v56
	v_add_f32_e32 v56, v60, v56
	v_cvt_pk_bf16_f32 v130, v60, v61
	v_add_f32_e32 v56, v61, v56
	v_add_f32_e32 v56, v62, v56
	v_cvt_pk_bf16_f32 v131, v62, v63
	v_add_f32_e32 v56, v63, v56
	v_add_f32_e32 v64, v64, v72
	v_add_f32_e32 v48, v48, v56
	v_add_f32_e32 v159, v48, v64
	s_waitcnt vmcnt(3)
	s_cmpk_gt_u32 s61, 0x81
	s_cbranch_scc1 .LBB0_1236
	s_add_i32 s10, s60, 0xffffe000
	s_and_b32 s10, s10, 0x4000
	v_add_u32_e32 v48, s10, v145
	s_add_i32 s10, s51, 0xffff
	s_mul_i32 s11, s10, 0xab
	s_bfe_u32 s11, s11, 0x70009
	s_mul_i32 s11, s11, 3
	s_sub_i32 s10, s10, s11
	s_and_b32 s10, s10, 0xff
	s_mulk_i32 s10, 0x4400
	s_add_i32 s16, s10, 0
	s_waitcnt vmcnt(5)
	ds_write_b128 v48, v[112:115]
	v_add_u32_e32 v48, s16, v144
	s_and_b64 vcc, exec, s[4:5]
	s_waitcnt vmcnt(4)
	ds_write_b128 v48, v[108:111] offset:32768
	s_cbranch_vccnz .LBB0_1236
	v_add_u32_e32 v48, s16, v150
	s_waitcnt vmcnt(3)
	ds_write_b128 v48, v[104:107] offset:32768

; #define SBAR() __builtin_amdgcn_sched_barrier(0)
; #define PK4(P, BASE, OUT) do { u32x4 w = {cvtpk_a(P[BASE + 0], P[BASE + 1]), cvtpk_a(P[BASE + 2], P[BASE + 3]), cvtpk_a(P[BASE + 4], P[BASE + 5]), cvtpk_a(P[BASE + 6], P[BASE + 7])}; \
;     OUT = *reinterpret_cast<bf16x8*>(&w); } while (0)
; #define SWAIT() asm volatile("s_waitcnt vmcnt(3)" ::: "memory")
; __device__ __forceinline__ float exp_pack(f32x16& p0, f32x16& p1, bf16x8& pa0, bf16x8& pa1, bf16x8& pa2, bf16x8& pa3) {
; #pragma unroll
;     for (int r = 0; r < 16; ++r) p0[r] = __builtin_amdgcn_exp2f(p0[r]);
; #pragma unroll
;     for (int r = 0; r < 16; ++r) p1[r] = __builtin_amdgcn_exp2f(p1[r]);
;     SBAR(); asm volatile("s_nop 1" ::: "memory"); SBAR();
;     ...
;     PK4(p0, 0, pa0); PK4(p0, 8, pa1); PK4(p1, 0, pa2); PK4(p1, 8, pa3);
;     ...
;     float ps0 = p0[0], ps1 = p1[0];
; #pragma unroll
;     for (int r = 1; r < 16; ++r) { ps0 += p0[r]; ps1 += p1[r]; }
;     float ps = ps0 + ps1;
;     { auto rr = __builtin_amdgcn_permlane32_swap(__float_as_uint(ps), __float_as_uint(ps), false, false);
;       ps = __uint_as_float(rr[0]) + __uint_as_float(rr[1]); }
;     return ps;
; template <bool MLA>
; __device__ __forceinline__ void attn_core(const bf16_t* __restrict__ Qb, const bf16_t* __restrict__ Kh, const bf16_t* __restrict__ Vh, int seq, char* lds,
;                                           f32x16 (&o)[Cfg<MLA>::NCB], const int wid  , const int g  ) {
;     ...
;         SWAIT(); if (j + 3 < NT) SWRITE(((j + 3) % 3) * SHM_K, ((j + 3) & 3) * SHM_V, SO);
.LBB0_1241:
	v_exp_f32_e32 v64, v64
	v_exp_f32_e32 v65, v65
	v_exp_f32_e32 v66, v66
	v_exp_f32_e32 v67, v67
	v_exp_f32_e32 v68, v68
	v_exp_f32_e32 v69, v69
	v_exp_f32_e32 v70, v70
	v_exp_f32_e32 v71, v71
	v_exp_f32_e32 v72, v72
	v_cvt_pk_bf16_f32 v140, v64, v65
	v_exp_f32_e32 v73, v73
	v_add_f32_e32 v64, v64, v65
	v_add_f32_e32 v64, v66, v64
	v_exp_f32_e32 v74, v74
	v_cvt_pk_bf16_f32 v141, v66, v67
	v_exp_f32_e32 v75, v75
	v_add_f32_e32 v64, v67, v64
	v_add_f32_e32 v64, v68, v64
	v_exp_f32_e32 v76, v76
	v_cvt_pk_bf16_f32 v142, v68, v69
	v_exp_f32_e32 v77, v77
	v_add_f32_e32 v64, v69, v64
	v_add_f32_e32 v64, v70, v64
	v_exp_f32_e32 v78, v78
	v_cvt_pk_bf16_f32 v143, v70, v71
	v_exp_f32_e32 v79, v79
	v_add_f32_e32 v64, v71, v64
	v_exp_f32_e32 v48, v48
	v_cvt_pk_bf16_f32 v136, v72, v73
	v_exp_f32_e32 v49, v49
	v_add_f32_e32 v72, v72, v73
	v_add_f32_e32 v72, v74, v72
	v_exp_f32_e32 v50, v50
	v_cvt_pk_bf16_f32 v137, v74, v75
	v_exp_f32_e32 v51, v51
	v_add_f32_e32 v72, v75, v72
	v_add_f32_e32 v72, v76, v72
	v_exp_f32_e32 v52, v52
	v_cvt_pk_bf16_f32 v138, v76, v77
	v_exp_f32_e32 v53, v53
	v_add_f32_e32 v72, v77, v72
	v_add_f32_e32 v72, v78, v72
	v_exp_f32_e32 v54, v54
	v_cvt_pk_bf16_f32 v139, v78, v79
	v_exp_f32_e32 v55, v55
	v_add_f32_e32 v72, v79, v72
	v_exp_f32_e32 v56, v56
	v_cvt_pk_bf16_f32 v132, v48, v49
	v_exp_f32_e32 v57, v57
	v_add_f32_e32 v48, v48, v49
	v_add_f32_e32 v48, v50, v48
	v_exp_f32_e32 v58, v58
	v_cvt_pk_bf16_f32 v133, v50, v51
	v_exp_f32_e32 v59, v59
	v_add_f32_e32 v48, v51, v48
	v_add_f32_e32 v48, v52, v48
	v_exp_f32_e32 v60, v60
	v_cvt_pk_bf16_f32 v134, v52, v53
	v_exp_f32_e32 v61, v61
	v_add_f32_e32 v48, v53, v48
	v_add_f32_e32 v48, v54, v48
	v_exp_f32_e32 v62, v62
	v_cvt_pk_bf16_f32 v135, v54, v55
	v_exp_f32_e32 v63, v63
	v_add_f32_e32 v48, v55, v48
	v_cvt_pk_bf16_f32 v128, v56, v57
	v_add_f32_e32 v56, v56, v57
	v_add_f32_e32 v56, v58, v56
	v_cvt_pk_bf16_f32 v129, v58, v59
	v_add_f32_e32 v56, v59, v56
	v_add_f32_e32 v56, v60, v56
	v_cvt_pk_bf16_f32 v130, v60, v61
	v_add_f32_e32 v56, v61, v56
	v_add_f32_e32 v56, v62, v56
	v_cvt_pk_bf16_f32 v131, v62, v63
	v_add_f32_e32 v56, v63, v56
	v_add_f32_e32 v64, v64, v72
	v_add_f32_e32 v48, v48, v56
	v_add_f32_e32 v48, v48, v64
	s_waitcnt vmcnt(3)
	s_cmpk_gt_u32 s61, 0x80
	s_cbranch_scc1 .LBB0_1227
	s_mul_i32 s10, s51, 0xab
	s_bfe_u32 s10, s10, 0x70009
	s_mul_i32 s10, s10, 3
	s_sub_i32 s10, s51, s10
	s_and_b32 s10, s10, 0xff
	s_mulk_i32 s10, 0x4400
	v_add_u32_e32 v50, s62, v145
	s_add_i32 s16, s10, 0
	s_waitcnt vmcnt(5)
	ds_write_b128 v50, v[116:119]
	v_add_u32_e32 v50, s16, v144
	s_and_b64 vcc, exec, s[4:5]
	s_waitcnt vmcnt(4)
	ds_write_b128 v50, v[124:127] offset:32768
	s_cbranch_vccnz .LBB0_1227
	v_add_u32_e32 v50, s16, v150
	s_waitcnt vmcnt(3)
	ds_write_b128 v50, v[120:123] offset:32768
	s_branch .LBB0_1227
